# phase-7 FFN-up epilogue rewritten by hand on a row-permuted A tile (conv taps become register-local, 16x fewer DPP moves)
# speedup vs baseline: 1.0314x; 1.0089x over previous
.LBB0_72:
	s_mov_b32 s58, s70
	s_waitcnt vmcnt(0)
	v_mov_b32_e32 v13, v197
	s_waitcnt vmcnt(0) lgkmcnt(0)
	s_barrier
	s_cmpk_gt_i32 s58, 0xaff
	v_readfirstlane_b32 s59, v13
	s_cbranch_scc1 .LBB0_92
	v_lshlrev_b32_e32 v1, 4, v13
	v_add_u32_e32 v0, 0x2000, v1
	v_ashrrev_i32_e32 v2, 31, v0
	v_lshrrev_b32_e32 v2, 22, v2
	v_add_u32_e32 v2, v0, v2
	v_ashrrev_i32_e32 v12, 10, v2
	v_mul_i32_i24_e32 v2, 0x400, v12
	v_sub_u32_e32 v0, v0, v2
	v_lshrrev_b32_e32 v2, 4, v0
	v_bitop3_b32 v0, v2, v0, 32 bitop3:0x6c
	s_load_dword s0, s[80:81], 0x10
	v_ashrrev_i32_e32 v2, 31, v0
	v_lshrrev_b32_e32 v2, 26, v2
	v_add_u32_e32 v2, v0, v2
	v_lshlrev_b32_e32 v4, 3, v12
	v_ashrrev_i32_e32 v14, 6, v2
	v_and_b32_e32 v4, -16, v4
	v_add_u32_e32 v4, v14, v4
	s_waitcnt lgkmcnt(0)
	s_lshr_b32 s22, s0, 16
	v_and_b32_e32 v5, 3, v14
	s_mov_b32 s0, 0x1fffe0
	v_lshrrev_b32_e32 v6, 2, v4
	v_lshlrev_b32_e32 v7, 1, v4
	v_and_b32_e32 v2, 0xc0, v2
	v_and_or_b32 v5, v4, s0, v5
	v_and_b32_e32 v6, 4, v6
	v_and_b32_e32 v7, 24, v7
	v_sub_u32_e32 v0, v0, v2
	v_or3_b32 v5, v5, v6, v7
	v_lshlrev_b32_e32 v6, 5, v12
	v_ashrrev_i16_sdwa v0, v221, sext(v0) dst_sel:DWORD dst_unused:UNUSED_PAD src0_sel:DWORD src1_sel:BYTE_0
	v_and_b32_e32 v6, 32, v6
	v_bfe_i32 v15, v0, 0, 16
	v_add_lshl_u32 v2, v6, v15, 1
	v_lshl_add_u32 v0, v5, 11, v2
	v_lshl_add_u32 v202, v4, 11, v2
	v_bfe_u32 v20, v202, 11, 4
	v_bfe_u32 v21, v202, 15, 2
	v_and_b32_e32 v202, 0xfffe07ff, v202
	v_lshl_or_b32 v202, v20, 13, v202
	v_lshl_or_b32 v202, v21, 11, v202
	v_bfe_i32 v2, v13, 27, 1
	v_lshrrev_b32_e32 v2, 22, v2
	v_add_u32_e32 v2, v1, v2
	v_and_b32_e32 v2, 0xfffffc00, v2
	v_sub_u32_e32 v1, v1, v2
	v_lshrrev_b32_e32 v2, 4, v1
	v_bitop3_b32 v2, v2, v1, 32 bitop3:0x6c
	v_ashrrev_i32_e32 v1, 31, v1
	v_lshrrev_b32_e32 v1, 26, v1
	v_add_u32_e32 v1, v2, v1
	v_ashrrev_i32_e32 v16, 6, v1
	v_ashrrev_i32_e32 v1, 31, v13
	v_lshrrev_b32_e32 v1, 26, v1
	v_add_u32_e32 v1, v13, v1
	v_ashrrev_i32_e32 v17, 6, v1
	v_lshlrev_b32_e32 v1, 3, v17
	v_and_b32_e32 v1, -16, v1
	v_add_u32_e32 v1, v16, v1
	v_and_b32_e32 v4, 3, v16
	s_ashr_i32 s61, s58, 31
	v_and_or_b32 v4, v1, s0, v4
	s_lshr_b32 s0, s61, 29
	s_add_i32 s0, s58, s0
	s_ashr_i32 s1, s59, 6
	s_ashr_i32 s23, s0, 3
	s_and_b32 s0, s0, -8
	s_ashr_i32 s21, s59, 8
	s_lshl_b32 s60, s1, 10
	s_sub_i32 s0, s58, s0
	s_cmp_lt_i32 s0, 0
	s_movk_i32 s4, 0x161
	s_cselect_b32 s24, s4, 0x160
	s_mul_i32 s0, s24, s0
	s_add_i32 s0, s0, s23
	s_mul_hi_i32 s23, s0, 0x2e8ba2e9
	s_lshr_b32 s24, s23, 31
	s_ashr_i32 s23, s23, 5
	s_add_i32 s23, s23, s24
	s_lshl_b32 s24, s23, 3
	s_mulk_i32 s23, 0xb0
	s_sub_i32 s23, s0, s23
	s_bfe_u32 s0, s23, 0x3001c
	s_add_i32 s25, s23, s0
	s_sext_i32_i16 s0, s25
	s_and_b32 s25, s25, 0xfff8
	s_sub_i32 s23, s23, s25
	s_sext_i32_i16 s23, s23
	s_add_i32 s50, s24, s23
	v_lshrrev_b32_e32 v5, 2, v1
	v_lshlrev_b32_e32 v6, 1, v1
	s_ashr_i32 s51, s50, 31
	v_and_b32_e32 v5, 4, v5
	v_and_b32_e32 v6, 24, v6
	s_lshr_b32 s0, s0, 3
	s_lshl_b64 s[24:25], s[50:51], 19
	v_readlane_b32 s26, v252, 10
	v_or3_b32 v4, v4, v5, v6
	v_mul_i32_i24_e32 v6, 64, v16
	v_readlane_b32 s27, v252, 11
	s_add_u32 s52, s26, s24
	v_sub_u32_e32 v2, v2, v6
	s_addc_u32 s53, s27, s25
	s_bfe_i64 s[24:25], s[0:1], 0x100000
	v_lshlrev_b32_e32 v5, 5, v17
	v_ashrrev_i16_sdwa v2, v221, sext(v2) dst_sel:DWORD dst_unused:UNUSED_PAD src0_sel:DWORD src1_sel:BYTE_0
	s_lshl_b64 s[24:25], s[24:25], 19
	v_readlane_b32 s26, v252, 18
	v_and_b32_e32 v5, 32, v5
	v_bfe_i32 v18, v2, 0, 16
	v_readlane_b32 s27, v252, 19
	s_add_u32 s54, s26, s24
	v_add_lshl_u32 v5, v5, v18, 1
	s_addc_u32 s55, s27, s25
	s_add_i32 s62, s60, 0
	v_lshl_add_u32 v2, v4, 11, v5
	s_add_i32 m0, s62, 0x10000
	v_lshl_add_u32 v204, v1, 11, v5
	v_bfe_u32 v20, v204, 11, 4
	v_bfe_u32 v21, v204, 15, 2
	v_and_b32_e32 v204, 0xfffe07ff, v204
	v_lshl_or_b32 v204, v20, 13, v204
	v_lshl_or_b32 v204, v21, 11, v204
	global_load_lds_dwordx4 v2, s[54:55]
	s_add_i32 m0, s62, 0x12000
	s_add_i32 s63, s62, 0x2000
	global_load_lds_dwordx4 v0, s[54:55]
	s_mov_b32 m0, s62
	s_add_u32 s24, s54, 0x40000
	global_load_lds_dwordx4 v204, s[52:53]
	s_mov_b32 m0, s63
	s_addc_u32 s25, s55, 0
	global_load_lds_dwordx4 v202, s[52:53]
	s_add_i32 m0, s62, 0x14000
	v_mov_b32_e32 v1, v3
	global_load_lds_dwordx4 v2, s[24:25]
	s_add_i32 m0, s62, 0x16000
	v_mov_b32_e32 v205, v3
	global_load_lds_dwordx4 v0, s[24:25]
	s_add_u32 s24, s52, 0x40000
	s_addc_u32 s25, s53, 0
	s_add_i32 s64, s62, 0x4000
	s_mov_b32 m0, s64
	s_add_i32 s65, s62, 0x6000
	global_load_lds_dwordx4 v204, s[24:25]
	s_mov_b32 m0, s65
	v_mov_b32_e32 v203, v3
	global_load_lds_dwordx4 v202, s[24:25]
	v_lshl_add_u64 v[10:11], s[54:55], 0, v[2:3]
	v_lshl_add_u64 v[8:9], s[54:55], 0, v[0:1]
	v_lshl_add_u64 v[6:7], s[52:53], 0, v[204:205]
	s_cmp_lg_u32 s21, 1
	v_lshl_add_u64 v[4:5], s[52:53], 0, v[202:203]
	s_cbranch_scc1 .LBB0_75
	s_barrier
.LBB0_75:
	s_and_b32 s22, 0xffff, s22
	s_cmp_lg_u32 s22, 0
	s_cselect_b64 s[22:23], -1, 0
	s_cmp_lg_u64 s[22:23], 0
	s_addc_u32 s66, s20, 0
	s_lshl_b32 s1, s1, 5
	s_and_b32 s1, s1, 0x60
	s_add_i32 m0, s62, 0x18000
	v_lshl_add_u64 v[10:11], v[10:11], 0, s[76:77]
	s_lshl_b32 s67, s21, 6
	s_lshl_b32 s22, s21, 13
	s_lshl_b32 s23, s1, 7
	s_waitcnt vmcnt(4)
	s_barrier
	global_load_lds_dwordx4 v[10:11], off
	v_lshl_add_u64 v[8:9], v[8:9], 0, s[76:77]
	s_add_i32 m0, s62, 0x1a000
	s_add_i32 s72, s62, 0x8000
	s_add_i32 s74, s62, 0xa000
	global_load_lds_dwordx4 v[8:9], off
	v_lshl_add_u64 v[6:7], v[6:7], 0, s[76:77]
	s_mov_b32 m0, s72
	s_add_u32 s20, s54, 0x40080
	global_load_lds_dwordx4 v[6:7], off
	v_lshl_add_u64 v[4:5], v[4:5], 0, s[76:77]
	s_mov_b32 m0, s74
	s_addc_u32 s21, s55, 0
	global_load_lds_dwordx4 v[4:5], off
	s_add_i32 m0, s62, 0x1c000
	v_lshl_add_u64 v[4:5], s[20:21], 0, v[2:3]
	global_load_lds_dwordx4 v[4:5], off
	v_lshl_add_u64 v[4:5], s[20:21], 0, v[0:1]
	s_add_i32 m0, s62, 0x1e000
	v_and_b32_e32 v201, 15, v13
	global_load_lds_dwordx4 v[4:5], off
	v_lshrrev_b32_e32 v4, 1, v13
	v_and_b32_e32 v4, 24, v4
	v_lshlrev_b32_e32 v5, 1, v4
	v_lshlrev_b32_e32 v6, 2, v13
	v_or_b32_e32 v238, s1, v4
	v_lshlrev_b32_e32 v4, 14, v17
	v_lshl_or_b32 v5, v201, 6, v5
	v_and_b32_e32 v6, 32, v6
	v_and_b32_e32 v4, 0xffff8000, v4
	v_bitop3_b32 v7, v5, s22, v6 bitop3:0xde
	v_bitop3_b32 v235, v5, s23, v6 bitop3:0xde
	v_lshl_add_u32 v4, v16, 11, v4
	v_and_b32_e32 v5, 1, v17
	v_lshl_or_b32 v4, v5, 6, v4
	v_lshl_add_u32 v206, v18, 1, v4
	v_bfe_u32 v20, v206, 11, 4
	v_bfe_u32 v21, v206, 15, 2
	v_and_b32_e32 v206, 0xfffe07ff, v206
	v_lshl_or_b32 v206, v20, 13, v206
	v_lshl_or_b32 v206, v21, 11, v206
	v_lshlrev_b32_e32 v4, 14, v12
	v_and_b32_e32 v4, 0xffff8000, v4
	s_waitcnt vmcnt(6)
	v_lshl_add_u32 v4, v14, 11, v4
	v_and_b32_e32 v5, 1, v12
	v_lshl_or_b32 v4, v5, 6, v4
	s_sext_i32_i16 s30, s0
	s_mov_b32 s75, 0
	v_cmp_gt_u32_e64 s[38:39], 2, v201
	v_cmp_lt_u32_e64 s[40:41], 13, v201
	v_add_u32_e32 v236, -14, v201
	v_or_b32_e32 v237, 2, v201
	s_ashr_i32 s80, s66, 31
	v_mov_b32_e32 v207, v3
	v_lshl_add_u32 v208, v15, 1, v4
	v_bfe_u32 v20, v208, 11, 4
	v_bfe_u32 v21, v208, 15, 2
	v_and_b32_e32 v208, 0xfffe07ff, v208
	v_lshl_or_b32 v208, v20, 13, v208
	v_lshl_or_b32 v208, v21, 11, v208
	v_mov_b32_e32 v209, v3
	v_add_u32_e32 v239, 0, v7
	s_mov_b64 s[48:49], s[54:55]
	s_mov_b64 s[46:47], s[52:53]
	s_barrier
	s_branch .LBB0_77

.LBB0_80:
	s_add_u32 s22, s52, 0xfffc0080
	s_addc_u32 s23, s53, -1
	s_add_i32 s24, 0, 0x10000
	v_add_u32_e32 v64, s24, v235
	ds_read_b128 v[52:55], v64
	ds_read_b128 v[56:59], v64 offset:1024
	ds_read_b128 v[60:63], v64 offset:2048
	ds_read_b128 v[64:67], v64 offset:3072
	s_cmp_eq_u32 s21, 12
	s_cselect_b32 s57, s47, s23
	s_cselect_b32 s56, s46, s22
	s_cselect_b32 s55, s49, s20
	s_cselect_b32 s54, s48, s1
	v_lshl_add_u64 v[116:117], s[52:53], 0, v[206:207]
	s_add_i32 m0, s62, 0xc000
	ds_read_b128 v[76:79], v239
	ds_read_b128 v[80:83], v239 offset:1024
	ds_read_b128 v[84:87], v239 offset:2048
	ds_read_b128 v[88:91], v239 offset:3072
	ds_read_b128 v[92:95], v239 offset:4096
	ds_read_b128 v[96:99], v239 offset:5120
	ds_read_b128 v[100:103], v239 offset:6144
	ds_read_b128 v[104:107], v239 offset:7168
	global_load_lds_dwordx4 v[116:117], off
	v_lshl_add_u64 v[116:117], s[52:53], 0, v[208:209]
	s_add_i32 m0, s62, 0xe000
	s_nop 0
	global_load_lds_dwordx4 v[116:117], off
	s_waitcnt lgkmcnt(8)
	s_barrier
	s_waitcnt lgkmcnt(0)
	s_setprio 1
	s_waitcnt lgkmcnt(0)
	v_mfma_f32_16x16x32_bf16 v[160:163], v[52:55], v[92:95], v[160:163]
	v_mfma_f32_16x16x32_bf16 v[152:155], v[60:63], v[92:95], v[152:155]
	v_mfma_f32_16x16x32_bf16 v[144:147], v[52:55], v[100:103], v[144:147]
	v_mfma_f32_16x16x32_bf16 v[140:143], v[60:63], v[100:103], v[140:143]
	v_mfma_f32_16x16x32_bf16 v[116:119], v[52:55], v[76:79], v[192:195]
	v_mfma_f32_16x16x32_bf16 v[120:123], v[60:63], v[76:79], v[184:187]
	v_mfma_f32_16x16x32_bf16 v[124:127], v[52:55], v[84:87], v[176:179]
	v_mfma_f32_16x16x32_bf16 v[128:131], v[60:63], v[84:87], v[168:171]
	v_mfma_f32_16x16x32_bf16 v[160:163], v[56:59], v[96:99], v[160:163]
	v_mfma_f32_16x16x32_bf16 v[152:155], v[64:67], v[96:99], v[152:155]
	v_mfma_f32_16x16x32_bf16 v[144:147], v[56:59], v[104:107], v[144:147]
	v_mfma_f32_16x16x32_bf16 v[140:143], v[64:67], v[104:107], v[140:143]
	v_mfma_f32_16x16x32_bf16 v[116:119], v[56:59], v[80:83], v[116:119]
	v_mfma_f32_16x16x32_bf16 v[120:123], v[64:67], v[80:83], v[120:123]
	v_mfma_f32_16x16x32_bf16 v[124:127], v[56:59], v[88:91], v[124:127]
	v_mfma_f32_16x16x32_bf16 v[128:131], v[64:67], v[88:91], v[128:131]
	s_setprio 0
	s_barrier
	s_add_i32 s25, 0, 0x14000
	s_add_i32 s22, s24, s60
	v_add_u32_e32 v192, s25, v235
	v_lshl_add_u64 v[198:199], s[54:55], 0, v[2:3]
	s_mov_b32 m0, s22
	ds_read_b128 v[168:171], v192
	ds_read_b128 v[176:179], v192 offset:1024
	ds_read_b128 v[184:187], v192 offset:2048
	ds_read_b128 v[192:195], v192 offset:3072
	global_load_lds_dwordx4 v[198:199], off
	v_lshl_add_u64 v[222:223], s[54:55], 0, v[0:1]
	s_add_i32 m0, s22, 0x2000
	s_nop 0
	global_load_lds_dwordx4 v[222:223], off
	s_barrier
	s_waitcnt lgkmcnt(0)
	s_setprio 1
	s_waitcnt lgkmcnt(0)
	v_mfma_f32_16x16x32_bf16 v[188:191], v[168:171], v[76:79], v[188:191]
	v_mfma_f32_16x16x32_bf16 v[76:79], v[184:187], v[76:79], v[180:183]
	v_mfma_f32_16x16x32_bf16 v[188:191], v[176:179], v[80:83], v[188:191]
	v_mfma_f32_16x16x32_bf16 v[76:79], v[192:195], v[80:83], v[76:79]
	v_mfma_f32_16x16x32_bf16 v[80:83], v[168:171], v[84:87], v[172:175]
	v_mfma_f32_16x16x32_bf16 v[84:87], v[184:187], v[84:87], v[164:167]
	v_mfma_f32_16x16x32_bf16 v[80:83], v[176:179], v[88:91], v[80:83]
	v_mfma_f32_16x16x32_bf16 v[84:87], v[192:195], v[88:91], v[84:87]
	v_mfma_f32_16x16x32_bf16 v[88:91], v[168:171], v[92:95], v[156:159]
	v_mfma_f32_16x16x32_bf16 v[92:95], v[184:187], v[92:95], v[148:151]
	v_mfma_f32_16x16x32_bf16 v[88:91], v[176:179], v[96:99], v[88:91]
	v_mfma_f32_16x16x32_bf16 v[92:95], v[192:195], v[96:99], v[92:95]
	v_mfma_f32_16x16x32_bf16 v[96:99], v[168:171], v[100:103], v[136:139]
	v_mfma_f32_16x16x32_bf16 v[100:103], v[184:187], v[100:103], v[132:135]
	v_mfma_f32_16x16x32_bf16 v[96:99], v[176:179], v[104:107], v[96:99]
	v_mfma_f32_16x16x32_bf16 v[100:103], v[192:195], v[104:107], v[100:103]
	s_setprio 0
	s_mov_b32 m0, s62
	v_lshl_add_u64 v[248:249], s[56:57], 0, v[204:205]
	s_barrier
	ds_read_b128 v[104:107], v239 offset:16384
	ds_read_b128 v[132:135], v239 offset:17408
	ds_read_b128 v[136:139], v239 offset:18432
	ds_read_b128 v[148:151], v239 offset:19456
	ds_read_b128 v[156:159], v239 offset:20480
	ds_read_b128 v[164:167], v239 offset:21504
	ds_read_b128 v[172:175], v239 offset:22528
	ds_read_b128 v[180:183], v239 offset:23552
	global_load_lds_dwordx4 v[248:249], off
	v_lshl_add_u64 v[250:251], s[56:57], 0, v[202:203]
	s_mov_b32 m0, s63
	s_nop 0
	global_load_lds_dwordx4 v[250:251], off
	s_barrier
	s_waitcnt lgkmcnt(0)
	s_setprio 1
	s_waitcnt lgkmcnt(0)
	v_mfma_f32_16x16x32_bf16 v[112:115], v[52:55], v[104:107], v[112:115]
	v_mfma_f32_16x16x32_bf16 v[72:75], v[60:63], v[104:107], v[72:75]
	v_mfma_f32_16x16x32_bf16 v[48:51], v[52:55], v[136:139], v[48:51]
	v_mfma_f32_16x16x32_bf16 v[40:43], v[60:63], v[136:139], v[40:43]
	v_mfma_f32_16x16x32_bf16 v[32:35], v[52:55], v[156:159], v[32:35]
	v_mfma_f32_16x16x32_bf16 v[24:27], v[60:63], v[156:159], v[24:27]
	v_mfma_f32_16x16x32_bf16 v[16:19], v[52:55], v[172:175], v[16:19]
	v_mfma_f32_16x16x32_bf16 v[12:15], v[60:63], v[172:175], v[12:15]
	v_mfma_f32_16x16x32_bf16 v[112:115], v[56:59], v[132:135], v[112:115]
	v_mfma_f32_16x16x32_bf16 v[72:75], v[64:67], v[132:135], v[72:75]
	v_mfma_f32_16x16x32_bf16 v[48:51], v[56:59], v[148:151], v[48:51]
	v_mfma_f32_16x16x32_bf16 v[40:43], v[64:67], v[148:151], v[40:43]
	v_mfma_f32_16x16x32_bf16 v[32:35], v[56:59], v[164:167], v[32:35]
	v_mfma_f32_16x16x32_bf16 v[24:27], v[64:67], v[164:167], v[24:27]
	v_mfma_f32_16x16x32_bf16 v[16:19], v[56:59], v[180:183], v[16:19]
	v_mfma_f32_16x16x32_bf16 v[12:15], v[64:67], v[180:183], v[12:15]
	s_setprio 0
	s_barrier
	s_add_u32 s22, s54, 0x40000
	s_addc_u32 s23, s55, 0
	s_add_i32 s24, s25, s60
	v_lshl_add_u64 v[52:53], s[22:23], 0, v[2:3]
	s_mov_b32 m0, s24
	s_nop 0
	global_load_lds_dwordx4 v[52:53], off
	v_lshl_add_u64 v[52:53], s[22:23], 0, v[0:1]
	s_add_i32 m0, s24, 0x2000
	s_nop 0
	global_load_lds_dwordx4 v[52:53], off
	s_waitcnt vmcnt(6)
	s_barrier
	s_setprio 1
	v_mfma_f32_16x16x32_bf16 v[44:47], v[168:171], v[136:139], v[44:47]
	v_mfma_f32_16x16x32_bf16 v[36:39], v[184:187], v[136:139], v[36:39]
	v_mfma_f32_16x16x32_bf16 v[28:31], v[168:171], v[156:159], v[28:31]
	v_mfma_f32_16x16x32_bf16 v[20:23], v[184:187], v[156:159], v[20:23]
	v_mfma_f32_16x16x32_bf16 v[8:11], v[168:171], v[172:175], v[8:11]
	v_mfma_f32_16x16x32_bf16 v[4:7], v[184:187], v[172:175], v[4:7]
	v_mfma_f32_16x16x32_bf16 v[52:55], v[168:171], v[104:107], v[108:111]
	v_mfma_f32_16x16x32_bf16 v[56:59], v[184:187], v[104:107], v[68:71]
	v_mfma_f32_16x16x32_bf16 v[44:47], v[176:179], v[148:151], v[44:47]
	v_mfma_f32_16x16x32_bf16 v[36:39], v[192:195], v[148:151], v[36:39]
	v_mfma_f32_16x16x32_bf16 v[28:31], v[176:179], v[164:167], v[28:31]
	v_mfma_f32_16x16x32_bf16 v[20:23], v[192:195], v[164:167], v[20:23]
	v_mfma_f32_16x16x32_bf16 v[8:11], v[176:179], v[180:183], v[8:11]
	v_mfma_f32_16x16x32_bf16 v[4:7], v[192:195], v[180:183], v[4:7]
	v_mfma_f32_16x16x32_bf16 v[52:55], v[176:179], v[132:135], v[52:55]
	v_mfma_f32_16x16x32_bf16 v[56:59], v[192:195], v[132:135], v[56:59]
	s_setprio 0
	s_add_i32 s24, 0, 0x18000
	v_add_u32_e32 v104, s24, v235
	s_barrier
	ds_read_b128 v[60:63], v104
	ds_read_b128 v[64:67], v104 offset:1024
	ds_read_b128 v[68:71], v104 offset:2048
	ds_read_b128 v[104:107], v104 offset:3072
	s_add_u32 s22, s56, 0x40000
	s_addc_u32 s23, s57, 0
	s_mov_b32 m0, s64
	v_lshl_add_u64 v[156:157], s[22:23], 0, v[204:205]
	ds_read_b128 v[108:111], v239 offset:32768
	ds_read_b128 v[132:135], v239 offset:33792
	ds_read_b128 v[136:139], v239 offset:34816
	ds_read_b128 v[148:151], v239 offset:35840
	ds_read_b128 v[210:213], v239 offset:36864
	ds_read_b128 v[214:217], v239 offset:37888
	ds_read_b128 v[240:243], v239 offset:38912
	ds_read_b128 v[244:247], v239 offset:39936
	global_load_lds_dwordx4 v[156:157], off
	v_lshl_add_u64 v[156:157], s[22:23], 0, v[202:203]
	s_mov_b32 m0, s65
	s_nop 0
	global_load_lds_dwordx4 v[156:157], off
	s_waitcnt lgkmcnt(8)
	s_barrier
	s_waitcnt lgkmcnt(0)
	s_setprio 1
	s_waitcnt lgkmcnt(0)
	v_mfma_f32_16x16x32_bf16 v[116:119], v[60:63], v[108:111], v[116:119]
	v_mfma_f32_16x16x32_bf16 v[192:195], v[64:67], v[132:135], v[116:119]
	v_mfma_f32_16x16x32_bf16 v[116:119], v[68:71], v[108:111], v[120:123]
	v_mfma_f32_16x16x32_bf16 v[184:187], v[104:107], v[132:135], v[116:119]
	v_mfma_f32_16x16x32_bf16 v[116:119], v[60:63], v[136:139], v[124:127]
	v_mfma_f32_16x16x32_bf16 v[176:179], v[64:67], v[148:151], v[116:119]
	v_mfma_f32_16x16x32_bf16 v[116:119], v[68:71], v[136:139], v[128:131]
	v_mfma_f32_16x16x32_bf16 v[168:171], v[104:107], v[148:151], v[116:119]
	v_mfma_f32_16x16x32_bf16 v[116:119], v[60:63], v[210:213], v[160:163]
	v_mfma_f32_16x16x32_bf16 v[160:163], v[64:67], v[214:217], v[116:119]
	v_mfma_f32_16x16x32_bf16 v[116:119], v[68:71], v[210:213], v[152:155]
	v_mfma_f32_16x16x32_bf16 v[152:155], v[104:107], v[214:217], v[116:119]
	v_mfma_f32_16x16x32_bf16 v[116:119], v[60:63], v[240:243], v[144:147]
	v_mfma_f32_16x16x32_bf16 v[144:147], v[64:67], v[244:247], v[116:119]
	v_mfma_f32_16x16x32_bf16 v[116:119], v[68:71], v[240:243], v[140:143]
	v_mfma_f32_16x16x32_bf16 v[140:143], v[104:107], v[244:247], v[116:119]
	s_setprio 0
	s_barrier
	s_add_i32 s25, 0, 0x1c000
	s_add_i32 s22, s24, s60
	v_add_u32_e32 v128, s25, v235
	v_lshl_add_u64 v[156:157], v[198:199], 0, s[76:77]
	s_mov_b32 m0, s22
	ds_read_b128 v[116:119], v128
	ds_read_b128 v[120:123], v128 offset:1024
	ds_read_b128 v[124:127], v128 offset:2048
	ds_read_b128 v[128:131], v128 offset:3072
	global_load_lds_dwordx4 v[156:157], off
	v_lshl_add_u64 v[156:157], v[222:223], 0, s[76:77]
	s_add_i32 m0, s22, 0x2000
	s_nop 0
	global_load_lds_dwordx4 v[156:157], off
	s_barrier
	s_waitcnt lgkmcnt(0)
	s_setprio 1
	s_waitcnt lgkmcnt(0)
	v_mfma_f32_16x16x32_bf16 v[76:79], v[124:127], v[108:111], v[76:79]
	v_mfma_f32_16x16x32_bf16 v[180:183], v[128:131], v[132:135], v[76:79]
	v_mfma_f32_16x16x32_bf16 v[76:79], v[116:119], v[136:139], v[80:83]
	v_mfma_f32_16x16x32_bf16 v[172:175], v[120:123], v[148:151], v[76:79]
	v_mfma_f32_16x16x32_bf16 v[76:79], v[124:127], v[136:139], v[84:87]
	v_mfma_f32_16x16x32_bf16 v[156:159], v[116:119], v[108:111], v[188:191]
	v_mfma_f32_16x16x32_bf16 v[164:167], v[128:131], v[148:151], v[76:79]
	v_mfma_f32_16x16x32_bf16 v[76:79], v[116:119], v[210:213], v[88:91]
	v_mfma_f32_16x16x32_bf16 v[188:191], v[120:123], v[132:135], v[156:159]
	v_mfma_f32_16x16x32_bf16 v[156:159], v[120:123], v[214:217], v[76:79]
	v_mfma_f32_16x16x32_bf16 v[76:79], v[124:127], v[210:213], v[92:95]
	v_mfma_f32_16x16x32_bf16 v[148:151], v[128:131], v[214:217], v[76:79]
	v_mfma_f32_16x16x32_bf16 v[76:79], v[116:119], v[240:243], v[96:99]
	v_mfma_f32_16x16x32_bf16 v[136:139], v[120:123], v[244:247], v[76:79]
	v_mfma_f32_16x16x32_bf16 v[76:79], v[124:127], v[240:243], v[100:103]
	v_mfma_f32_16x16x32_bf16 v[132:135], v[128:131], v[244:247], v[76:79]
	s_setprio 0
	s_mov_b32 m0, s72
	v_lshl_add_u64 v[108:109], v[248:249], 0, s[76:77]
	s_barrier
	s_nop 2
	ds_read_b128 v[76:79], v239 offset:49152
	ds_read_b128 v[80:83], v239 offset:50176
	ds_read_b128 v[84:87], v239 offset:51200
	ds_read_b128 v[88:91], v239 offset:52224
	ds_read_b128 v[92:95], v239 offset:53248
	ds_read_b128 v[96:99], v239 offset:54272
	ds_read_b128 v[100:103], v239 offset:55296
	ds_read_b128 v[210:213], v239 offset:56320
	global_load_lds_dwordx4 v[108:109], off
	v_lshl_add_u64 v[108:109], v[250:251], 0, s[76:77]
	s_mov_b32 m0, s74
	s_nop 0
	global_load_lds_dwordx4 v[108:109], off
	s_barrier
	s_waitcnt lgkmcnt(0)
	s_setprio 1
	s_waitcnt lgkmcnt(0)
	v_mfma_f32_16x16x32_bf16 v[108:111], v[60:63], v[76:79], v[112:115]
	v_mfma_f32_16x16x32_bf16 v[72:75], v[68:71], v[76:79], v[72:75]
	v_mfma_f32_16x16x32_bf16 v[48:51], v[60:63], v[84:87], v[48:51]
	v_mfma_f32_16x16x32_bf16 v[40:43], v[68:71], v[84:87], v[40:43]
	v_mfma_f32_16x16x32_bf16 v[32:35], v[60:63], v[92:95], v[32:35]
	v_mfma_f32_16x16x32_bf16 v[24:27], v[68:71], v[92:95], v[24:27]
	v_mfma_f32_16x16x32_bf16 v[16:19], v[60:63], v[100:103], v[16:19]
	v_mfma_f32_16x16x32_bf16 v[12:15], v[68:71], v[100:103], v[12:15]
	v_mfma_f32_16x16x32_bf16 v[112:115], v[64:67], v[80:83], v[108:111]
	v_mfma_f32_16x16x32_bf16 v[72:75], v[104:107], v[80:83], v[72:75]
	v_mfma_f32_16x16x32_bf16 v[48:51], v[64:67], v[88:91], v[48:51]
	v_mfma_f32_16x16x32_bf16 v[40:43], v[104:107], v[88:91], v[40:43]
	v_mfma_f32_16x16x32_bf16 v[32:35], v[64:67], v[96:99], v[32:35]
	v_mfma_f32_16x16x32_bf16 v[24:27], v[104:107], v[96:99], v[24:27]
	v_mfma_f32_16x16x32_bf16 v[16:19], v[64:67], v[210:213], v[16:19]
	v_mfma_f32_16x16x32_bf16 v[12:15], v[104:107], v[210:213], v[12:15]
	s_setprio 0
	s_barrier
	s_add_u32 s22, s54, 0x40080
	s_addc_u32 s23, s55, 0
	s_add_i32 s24, s25, s60
	v_lshl_add_u64 v[60:61], s[22:23], 0, v[2:3]
	s_mov_b32 m0, s24
	s_nop 0
	global_load_lds_dwordx4 v[60:61], off
	v_lshl_add_u64 v[60:61], s[22:23], 0, v[0:1]
	s_add_i32 m0, s24, 0x2000
	s_nop 0
	global_load_lds_dwordx4 v[60:61], off
	s_waitcnt vmcnt(6)
	s_barrier
	s_setprio 1
	v_mfma_f32_16x16x32_bf16 v[52:55], v[116:119], v[76:79], v[52:55]
	v_mfma_f32_16x16x32_bf16 v[108:111], v[120:123], v[80:83], v[52:55]
	v_mfma_f32_16x16x32_bf16 v[52:55], v[124:127], v[76:79], v[56:59]
	v_mfma_f32_16x16x32_bf16 v[44:47], v[116:119], v[84:87], v[44:47]
	v_mfma_f32_16x16x32_bf16 v[36:39], v[124:127], v[84:87], v[36:39]
	v_mfma_f32_16x16x32_bf16 v[28:31], v[116:119], v[92:95], v[28:31]
	v_mfma_f32_16x16x32_bf16 v[20:23], v[124:127], v[92:95], v[20:23]
	v_mfma_f32_16x16x32_bf16 v[8:11], v[116:119], v[100:103], v[8:11]
	v_mfma_f32_16x16x32_bf16 v[4:7], v[124:127], v[100:103], v[4:7]
	v_mfma_f32_16x16x32_bf16 v[68:71], v[128:131], v[80:83], v[52:55]
	v_mfma_f32_16x16x32_bf16 v[44:47], v[120:123], v[88:91], v[44:47]
	v_mfma_f32_16x16x32_bf16 v[36:39], v[128:131], v[88:91], v[36:39]
	v_mfma_f32_16x16x32_bf16 v[28:31], v[120:123], v[96:99], v[28:31]
	v_mfma_f32_16x16x32_bf16 v[20:23], v[128:131], v[96:99], v[20:23]
	v_mfma_f32_16x16x32_bf16 v[8:11], v[120:123], v[210:213], v[8:11]
	v_mfma_f32_16x16x32_bf16 v[4:7], v[128:131], v[210:213], v[4:7]
	s_setprio 0
	s_add_i32 s21, s21, 2
	s_add_u32 s52, s52, 0x100
	s_addc_u32 s53, s53, 0
	s_add_u32 s1, s1, 0x100
	s_addc_u32 s20, s20, 0
	s_cmp_gt_u32 s21, 13
	s_barrier
	s_cbranch_scc0 .LBB0_80
	v_lshl_or_b32 v210, s30, 7, v238
	s_lshl_b32 s1, s50, 8
	s_add_i32 s1, s1, s67
	v_lshlrev_b32_e32 v211, 2, v210
	v_lshlrev_b32_e32 v219, 1, v210
	v_readlane_b32 s2, v252, 4
	v_readlane_b32 s3, v252, 5
	v_readlane_b32 s20, v252, 20
	v_readlane_b32 s21, v252, 21
	v_readlane_b32 s22, v252, 2
	v_readlane_b32 s23, v252, 3
	v_readlane_b32 s24, v252, 22
	v_readlane_b32 s25, v252, 23
	v_readlane_b32 s26, v252, 24
	v_readlane_b32 s27, v252, 25
	v_readlane_b32 s50, v252, 26
	v_readlane_b32 s51, v252, 27
	v_readlane_b32 s56, v252, 28
	v_readlane_b32 s57, v252, 29
	v_readlane_b32 s98, v252, 30
	v_readlane_b32 s99, v252, 31
	v_lshl_add_u32 v240, v201, 2, s1
	v_mul_u32_u24_e32 v240, 0x1600, v240
	v_add_u32_e32 v240, v240, v219
	global_load_dwordx4 v[120:123], v211, s[2:3]
	global_load_dwordx4 v[80:83], v211, s[2:3] offset:16
	global_load_dwordx4 v[116:119], v211, s[20:21]
	global_load_dwordx4 v[76:79], v211, s[20:21] offset:16
	global_load_dwordx4 v[96:99], v211, s[22:23]
	global_load_dwordx4 v[56:59], v211, s[22:23] offset:16
	global_load_dwordx4 v[92:95], v211, s[24:25]
	global_load_dwordx4 v[52:55], v211, s[24:25] offset:16
	global_load_dwordx4 v[104:107], v211, s[26:27]
	global_load_dwordx4 v[64:67], v211, s[26:27] offset:16
	global_load_dwordx4 v[100:103], v211, s[50:51]
	global_load_dwordx4 v[60:63], v211, s[50:51] offset:16
	global_load_dwordx4 v[124:127], v211, s[56:57]
	global_load_dwordx4 v[84:87], v211, s[56:57] offset:16
	global_load_dwordx4 v[128:131], v211, s[98:99]
	global_load_dwordx4 v[88:91], v211, s[98:99] offset:16
	v_readlane_b32 s56, v254, 63
	v_readlane_b32 s57, v255, 0
	v_cmp_eq_u32_e64 s[2:3], 0, v201
	v_cmp_eq_u32_e64 s[26:27], 15, v201
	s_lshr_b32 s24, s1, 4
	s_mov_b64 exec, s[2:3]
	v_cvt_pk_bf16_f32 v212, v192, v193
	v_cvt_pk_bf16_f32 v213, v194, v195
	v_cvt_pk_bf16_f32 v214, v184, v185
	v_cvt_pk_bf16_f32 v215, v186, v187
	s_add_i32 s20, s24, 2
	s_mulk_i32 s20, 0x2c00
	s_add_u32 s22, s56, s20
	s_addc_u32 s23, s57, 0
	global_store_dwordx4 v219, v[212:215], s[22:23]
	v_cvt_pk_bf16_f32 v242, v188, v189
	v_cvt_pk_bf16_f32 v243, v190, v191
	v_cvt_pk_bf16_f32 v244, v180, v181
	v_cvt_pk_bf16_f32 v245, v182, v183
	s_add_u32 s22, s22, 0x1600
	s_addc_u32 s23, s23, 0
	global_store_dwordx4 v219, v[242:245], s[22:23]
	v_cvt_pk_bf16_f32 v246, v176, v177
	v_cvt_pk_bf16_f32 v247, v178, v179
	v_cvt_pk_bf16_f32 v248, v168, v169
	v_cvt_pk_bf16_f32 v249, v170, v171
	s_add_i32 s20, s24, 3
	s_mulk_i32 s20, 0x2c00
	s_add_u32 s22, s56, s20
	s_addc_u32 s23, s57, 0
	global_store_dwordx4 v219, v[246:249], s[22:23]
	v_cvt_pk_bf16_f32 v212, v172, v173
	v_cvt_pk_bf16_f32 v213, v174, v175
	v_cvt_pk_bf16_f32 v214, v164, v165
	v_cvt_pk_bf16_f32 v215, v166, v167
	s_add_u32 s22, s22, 0x1600
	s_addc_u32 s23, s23, 0
	global_store_dwordx4 v219, v[212:215], s[22:23]
	s_mov_b64 exec, s[26:27]
	v_cvt_pk_bf16_f32 v242, v160, v161
	v_cvt_pk_bf16_f32 v243, v162, v163
	v_cvt_pk_bf16_f32 v244, v152, v153
	v_cvt_pk_bf16_f32 v245, v154, v155
	s_add_i32 s20, s24, 0
	s_mulk_i32 s20, 0x2c00
	s_add_u32 s22, s56, s20
	s_addc_u32 s23, s57, 0
	global_store_dwordx4 v219, v[242:245], s[22:23]
	v_cvt_pk_bf16_f32 v246, v156, v157
	v_cvt_pk_bf16_f32 v247, v158, v159
	v_cvt_pk_bf16_f32 v248, v148, v149
	v_cvt_pk_bf16_f32 v249, v150, v151
	s_add_u32 s22, s22, 0x1600
	s_addc_u32 s23, s23, 0
	global_store_dwordx4 v219, v[246:249], s[22:23]
	v_cvt_pk_bf16_f32 v212, v144, v145
	v_cvt_pk_bf16_f32 v213, v146, v147
	v_cvt_pk_bf16_f32 v214, v140, v141
	v_cvt_pk_bf16_f32 v215, v142, v143
	s_add_i32 s20, s24, 1
	s_mulk_i32 s20, 0x2c00
	s_add_u32 s22, s56, s20
	s_addc_u32 s23, s57, 0
	global_store_dwordx4 v219, v[212:215], s[22:23]
	v_cvt_pk_bf16_f32 v242, v136, v137
	v_cvt_pk_bf16_f32 v243, v138, v139
	v_cvt_pk_bf16_f32 v244, v132, v133
	v_cvt_pk_bf16_f32 v245, v134, v135
	s_add_u32 s22, s22, 0x1600
	s_addc_u32 s23, s23, 0
	global_store_dwordx4 v219, v[242:245], s[22:23]
	s_mov_b64 exec, s[2:3]
	v_cvt_pk_bf16_f32 v246, v112, v113
	v_cvt_pk_bf16_f32 v247, v114, v115
	v_cvt_pk_bf16_f32 v248, v72, v73
	v_cvt_pk_bf16_f32 v249, v74, v75
	s_add_i32 s20, s24, 10
	s_mulk_i32 s20, 0x2c00
	s_add_u32 s22, s56, s20
	s_addc_u32 s23, s57, 0
	global_store_dwordx4 v219, v[246:249], s[22:23]
	v_cvt_pk_bf16_f32 v212, v108, v109
	v_cvt_pk_bf16_f32 v213, v110, v111
	v_cvt_pk_bf16_f32 v214, v68, v69
	v_cvt_pk_bf16_f32 v215, v70, v71
	s_add_u32 s22, s22, 0x1600
	s_addc_u32 s23, s23, 0
	global_store_dwordx4 v219, v[212:215], s[22:23]
	v_cvt_pk_bf16_f32 v242, v48, v49
	v_cvt_pk_bf16_f32 v243, v50, v51
	v_cvt_pk_bf16_f32 v244, v40, v41
	v_cvt_pk_bf16_f32 v245, v42, v43
	s_add_i32 s20, s24, 11
	s_mulk_i32 s20, 0x2c00
	s_add_u32 s22, s56, s20
	s_addc_u32 s23, s57, 0
	global_store_dwordx4 v219, v[242:245], s[22:23]
	v_cvt_pk_bf16_f32 v246, v44, v45
	v_cvt_pk_bf16_f32 v247, v46, v47
	v_cvt_pk_bf16_f32 v248, v36, v37
	v_cvt_pk_bf16_f32 v249, v38, v39
	s_add_u32 s22, s22, 0x1600
	s_addc_u32 s23, s23, 0
	global_store_dwordx4 v219, v[246:249], s[22:23]
	s_mov_b64 exec, s[26:27]
	v_cvt_pk_bf16_f32 v212, v32, v33
	v_cvt_pk_bf16_f32 v213, v34, v35
	v_cvt_pk_bf16_f32 v214, v24, v25
	v_cvt_pk_bf16_f32 v215, v26, v27
	s_add_i32 s20, s24, 8
	s_mulk_i32 s20, 0x2c00
	s_add_u32 s22, s56, s20
	s_addc_u32 s23, s57, 0
	global_store_dwordx4 v219, v[212:215], s[22:23]
	v_cvt_pk_bf16_f32 v242, v28, v29
	v_cvt_pk_bf16_f32 v243, v30, v31
	v_cvt_pk_bf16_f32 v244, v20, v21
	v_cvt_pk_bf16_f32 v245, v22, v23
	s_add_u32 s22, s22, 0x1600
	s_addc_u32 s23, s23, 0
	global_store_dwordx4 v219, v[242:245], s[22:23]
	v_cvt_pk_bf16_f32 v246, v16, v17
	v_cvt_pk_bf16_f32 v247, v18, v19
	v_cvt_pk_bf16_f32 v248, v12, v13
	v_cvt_pk_bf16_f32 v249, v14, v15
	s_add_i32 s20, s24, 9
	s_mulk_i32 s20, 0x2c00
	s_add_u32 s22, s56, s20
	s_addc_u32 s23, s57, 0
	global_store_dwordx4 v219, v[246:249], s[22:23]
	v_cvt_pk_bf16_f32 v212, v8, v9
	v_cvt_pk_bf16_f32 v213, v10, v11
	v_cvt_pk_bf16_f32 v214, v4, v5
	v_cvt_pk_bf16_f32 v215, v6, v7
	s_add_u32 s22, s22, 0x1600
	s_addc_u32 s23, s23, 0
	global_store_dwordx4 v219, v[212:215], s[22:23]
	s_mov_b64 exec, -1
	s_mov_b32 s50, 0xbfb8aa3b
	s_mov_b32 s51, 0xbfb8aa3b
	s_waitcnt vmcnt(16)
	v_mov_b32_dpp v198, v144 row_shr:1 row_mask:0xf bank_mask:0xf bound_ctrl:1
	v_mov_b32_dpp v199, v145 row_shr:1 row_mask:0xf bank_mask:0xf bound_ctrl:1
	v_mov_b32_dpp v214, v136 row_shr:1 row_mask:0xf bank_mask:0xf bound_ctrl:1
	v_mov_b32_dpp v215, v137 row_shr:1 row_mask:0xf bank_mask:0xf bound_ctrl:1
	v_mov_b32_dpp v212, v160 row_shr:1 row_mask:0xf bank_mask:0xf bound_ctrl:1
	v_mov_b32_dpp v213, v161 row_shr:1 row_mask:0xf bank_mask:0xf bound_ctrl:1
	v_mov_b32_dpp v216, v156 row_shr:1 row_mask:0xf bank_mask:0xf bound_ctrl:1
	v_mov_b32_dpp v217, v157 row_shr:1 row_mask:0xf bank_mask:0xf bound_ctrl:1
	v_pk_fma_f32 v[144:145], v[144:145], v[124:125], v[120:121]
	v_pk_fma_f32 v[136:137], v[136:137], v[128:129], v[116:117]
	v_pk_fma_f32 v[144:145], v[160:161], v[104:105], v[144:145]
	v_pk_fma_f32 v[136:137], v[156:157], v[100:101], v[136:137]
	v_pk_fma_f32 v[144:145], v[176:177], v[96:97], v[144:145]
	v_pk_fma_f32 v[136:137], v[172:173], v[92:93], v[136:137]
	v_pk_fma_f32 v[160:161], v[160:161], v[124:125], v[120:121]
	v_pk_fma_f32 v[156:157], v[156:157], v[128:129], v[116:117]
	v_pk_fma_f32 v[160:161], v[176:177], v[104:105], v[160:161]
	v_pk_fma_f32 v[156:157], v[172:173], v[100:101], v[156:157]
	v_pk_fma_f32 v[160:161], v[192:193], v[96:97], v[160:161]
	v_pk_fma_f32 v[156:157], v[188:189], v[92:93], v[156:157]
	v_pk_fma_f32 v[176:177], v[176:177], v[124:125], v[120:121]
	v_pk_fma_f32 v[172:173], v[172:173], v[128:129], v[116:117]
	v_pk_fma_f32 v[176:177], v[192:193], v[104:105], v[176:177]
	v_pk_fma_f32 v[172:173], v[188:189], v[100:101], v[172:173]
	v_pk_fma_f32 v[176:177], v[198:199], v[96:97], v[176:177]
	v_pk_fma_f32 v[172:173], v[214:215], v[92:93], v[172:173]
	v_pk_fma_f32 v[192:193], v[192:193], v[124:125], v[120:121]
	v_pk_fma_f32 v[188:189], v[188:189], v[128:129], v[116:117]
	v_pk_fma_f32 v[192:193], v[198:199], v[104:105], v[192:193]
	v_pk_fma_f32 v[188:189], v[214:215], v[100:101], v[188:189]
	v_pk_fma_f32 v[192:193], v[212:213], v[96:97], v[192:193]
	v_pk_fma_f32 v[188:189], v[216:217], v[92:93], v[188:189]
	v_pk_mul_f32 v[222:223], v[192:193], s[50:51]
	v_pk_mul_f32 v[242:243], v[176:177], s[50:51]
	v_pk_mul_f32 v[244:245], v[160:161], s[50:51]
	v_pk_mul_f32 v[246:247], v[144:145], s[50:51]
	v_exp_f32_e32 v222, v222
	v_exp_f32_e32 v223, v223
	v_exp_f32_e32 v242, v242
	v_exp_f32_e32 v243, v243
	v_exp_f32_e32 v244, v244
	v_exp_f32_e32 v245, v245
	v_exp_f32_e32 v246, v246
	v_exp_f32_e32 v247, v247
	v_pk_add_f32 v[222:223], v[222:223], 1.0 op_sel_hi:[1,0]
	v_pk_add_f32 v[242:243], v[242:243], 1.0 op_sel_hi:[1,0]
	v_pk_add_f32 v[244:245], v[244:245], 1.0 op_sel_hi:[1,0]
	v_pk_add_f32 v[246:247], v[246:247], 1.0 op_sel_hi:[1,0]
	v_rcp_f32_e32 v222, v222
	v_rcp_f32_e32 v223, v223
	v_rcp_f32_e32 v242, v242
	v_rcp_f32_e32 v243, v243
	v_rcp_f32_e32 v244, v244
	v_rcp_f32_e32 v245, v245
	v_rcp_f32_e32 v246, v246
	v_rcp_f32_e32 v247, v247
	v_pk_mul_f32 v[192:193], v[192:193], v[222:223]
	v_pk_mul_f32 v[176:177], v[176:177], v[242:243]
	v_pk_mul_f32 v[160:161], v[160:161], v[244:245]
	v_pk_mul_f32 v[144:145], v[144:145], v[246:247]
	v_pk_mul_f32 v[192:193], v[192:193], v[188:189]
	v_pk_mul_f32 v[176:177], v[176:177], v[172:173]
	v_pk_mul_f32 v[160:161], v[160:161], v[156:157]
	v_pk_mul_f32 v[144:145], v[144:145], v[136:137]
	v_cvt_pk_bf16_f32 v192, v192, v193
	v_cvt_pk_bf16_f32 v176, v176, v177
	v_cvt_pk_bf16_f32 v160, v160, v161
	v_cvt_pk_bf16_f32 v144, v144, v145
	v_mov_b32_dpp v198, v146 row_shr:1 row_mask:0xf bank_mask:0xf bound_ctrl:1
	v_mov_b32_dpp v199, v147 row_shr:1 row_mask:0xf bank_mask:0xf bound_ctrl:1
	v_mov_b32_dpp v214, v138 row_shr:1 row_mask:0xf bank_mask:0xf bound_ctrl:1
	v_mov_b32_dpp v215, v139 row_shr:1 row_mask:0xf bank_mask:0xf bound_ctrl:1
	v_mov_b32_dpp v212, v162 row_shr:1 row_mask:0xf bank_mask:0xf bound_ctrl:1
	v_mov_b32_dpp v213, v163 row_shr:1 row_mask:0xf bank_mask:0xf bound_ctrl:1
	v_mov_b32_dpp v216, v158 row_shr:1 row_mask:0xf bank_mask:0xf bound_ctrl:1
	v_mov_b32_dpp v217, v159 row_shr:1 row_mask:0xf bank_mask:0xf bound_ctrl:1
	v_pk_fma_f32 v[146:147], v[146:147], v[126:127], v[122:123]
	v_pk_fma_f32 v[138:139], v[138:139], v[130:131], v[118:119]
	v_pk_fma_f32 v[146:147], v[162:163], v[106:107], v[146:147]
	v_pk_fma_f32 v[138:139], v[158:159], v[102:103], v[138:139]
	v_pk_fma_f32 v[146:147], v[178:179], v[98:99], v[146:147]
	v_pk_fma_f32 v[138:139], v[174:175], v[94:95], v[138:139]
	v_pk_fma_f32 v[162:163], v[162:163], v[126:127], v[122:123]
	v_pk_fma_f32 v[158:159], v[158:159], v[130:131], v[118:119]
	v_pk_fma_f32 v[162:163], v[178:179], v[106:107], v[162:163]
	v_pk_fma_f32 v[158:159], v[174:175], v[102:103], v[158:159]
	v_pk_fma_f32 v[162:163], v[194:195], v[98:99], v[162:163]
	v_pk_fma_f32 v[158:159], v[190:191], v[94:95], v[158:159]
	v_pk_fma_f32 v[178:179], v[178:179], v[126:127], v[122:123]
	v_pk_fma_f32 v[174:175], v[174:175], v[130:131], v[118:119]
	v_pk_fma_f32 v[178:179], v[194:195], v[106:107], v[178:179]
	v_pk_fma_f32 v[174:175], v[190:191], v[102:103], v[174:175]
	v_pk_fma_f32 v[178:179], v[198:199], v[98:99], v[178:179]
	v_pk_fma_f32 v[174:175], v[214:215], v[94:95], v[174:175]
	v_pk_fma_f32 v[194:195], v[194:195], v[126:127], v[122:123]
	v_pk_fma_f32 v[190:191], v[190:191], v[130:131], v[118:119]
	v_pk_fma_f32 v[194:195], v[198:199], v[106:107], v[194:195]
	v_pk_fma_f32 v[190:191], v[214:215], v[102:103], v[190:191]
	v_pk_fma_f32 v[194:195], v[212:213], v[98:99], v[194:195]
	v_pk_fma_f32 v[190:191], v[216:217], v[94:95], v[190:191]
	v_pk_mul_f32 v[222:223], v[194:195], s[50:51]
	v_pk_mul_f32 v[242:243], v[178:179], s[50:51]
	v_pk_mul_f32 v[244:245], v[162:163], s[50:51]
	v_pk_mul_f32 v[246:247], v[146:147], s[50:51]
	v_exp_f32_e32 v222, v222
	v_exp_f32_e32 v223, v223
	v_exp_f32_e32 v242, v242
	v_exp_f32_e32 v243, v243
	v_exp_f32_e32 v244, v244
	v_exp_f32_e32 v245, v245
	v_exp_f32_e32 v246, v246
	v_exp_f32_e32 v247, v247
	v_pk_add_f32 v[222:223], v[222:223], 1.0 op_sel_hi:[1,0]
	v_pk_add_f32 v[242:243], v[242:243], 1.0 op_sel_hi:[1,0]
	v_pk_add_f32 v[244:245], v[244:245], 1.0 op_sel_hi:[1,0]
	v_pk_add_f32 v[246:247], v[246:247], 1.0 op_sel_hi:[1,0]
	v_rcp_f32_e32 v222, v222
	v_rcp_f32_e32 v223, v223
	v_rcp_f32_e32 v242, v242
	v_rcp_f32_e32 v243, v243
	v_rcp_f32_e32 v244, v244
	v_rcp_f32_e32 v245, v245
	v_rcp_f32_e32 v246, v246
	v_rcp_f32_e32 v247, v247
	v_pk_mul_f32 v[194:195], v[194:195], v[222:223]
	v_pk_mul_f32 v[178:179], v[178:179], v[242:243]
	v_pk_mul_f32 v[162:163], v[162:163], v[244:245]
	v_pk_mul_f32 v[146:147], v[146:147], v[246:247]
	v_pk_mul_f32 v[194:195], v[194:195], v[190:191]
	v_pk_mul_f32 v[178:179], v[178:179], v[174:175]
	v_pk_mul_f32 v[162:163], v[162:163], v[158:159]
	v_pk_mul_f32 v[146:147], v[146:147], v[138:139]
	v_cvt_pk_bf16_f32 v193, v194, v195
	v_cvt_pk_bf16_f32 v177, v178, v179
	v_cvt_pk_bf16_f32 v161, v162, v163
	v_cvt_pk_bf16_f32 v145, v146, v147
	v_mov_b32_dpp v198, v140 row_shr:1 row_mask:0xf bank_mask:0xf bound_ctrl:1
	v_mov_b32_dpp v199, v141 row_shr:1 row_mask:0xf bank_mask:0xf bound_ctrl:1
	v_mov_b32_dpp v214, v132 row_shr:1 row_mask:0xf bank_mask:0xf bound_ctrl:1
	v_mov_b32_dpp v215, v133 row_shr:1 row_mask:0xf bank_mask:0xf bound_ctrl:1
	v_mov_b32_dpp v212, v152 row_shr:1 row_mask:0xf bank_mask:0xf bound_ctrl:1
	v_mov_b32_dpp v213, v153 row_shr:1 row_mask:0xf bank_mask:0xf bound_ctrl:1
	v_mov_b32_dpp v216, v148 row_shr:1 row_mask:0xf bank_mask:0xf bound_ctrl:1
	v_mov_b32_dpp v217, v149 row_shr:1 row_mask:0xf bank_mask:0xf bound_ctrl:1
	v_pk_fma_f32 v[140:141], v[140:141], v[84:85], v[80:81]
	v_pk_fma_f32 v[132:133], v[132:133], v[88:89], v[76:77]
	v_pk_fma_f32 v[140:141], v[152:153], v[64:65], v[140:141]
	v_pk_fma_f32 v[132:133], v[148:149], v[60:61], v[132:133]
	v_pk_fma_f32 v[140:141], v[168:169], v[56:57], v[140:141]
	v_pk_fma_f32 v[132:133], v[164:165], v[52:53], v[132:133]
	v_pk_fma_f32 v[152:153], v[152:153], v[84:85], v[80:81]
	v_pk_fma_f32 v[148:149], v[148:149], v[88:89], v[76:77]
	v_pk_fma_f32 v[152:153], v[168:169], v[64:65], v[152:153]
	v_pk_fma_f32 v[148:149], v[164:165], v[60:61], v[148:149]
	v_pk_fma_f32 v[152:153], v[184:185], v[56:57], v[152:153]
	v_pk_fma_f32 v[148:149], v[180:181], v[52:53], v[148:149]
	v_pk_fma_f32 v[168:169], v[168:169], v[84:85], v[80:81]
	v_pk_fma_f32 v[164:165], v[164:165], v[88:89], v[76:77]
	v_pk_fma_f32 v[168:169], v[184:185], v[64:65], v[168:169]
	v_pk_fma_f32 v[164:165], v[180:181], v[60:61], v[164:165]
	v_pk_fma_f32 v[168:169], v[198:199], v[56:57], v[168:169]
	v_pk_fma_f32 v[164:165], v[214:215], v[52:53], v[164:165]
	v_pk_fma_f32 v[184:185], v[184:185], v[84:85], v[80:81]
	v_pk_fma_f32 v[180:181], v[180:181], v[88:89], v[76:77]
	v_pk_fma_f32 v[184:185], v[198:199], v[64:65], v[184:185]
	v_pk_fma_f32 v[180:181], v[214:215], v[60:61], v[180:181]
	v_pk_fma_f32 v[184:185], v[212:213], v[56:57], v[184:185]
	v_pk_fma_f32 v[180:181], v[216:217], v[52:53], v[180:181]
	v_pk_mul_f32 v[222:223], v[184:185], s[50:51]
	v_pk_mul_f32 v[242:243], v[168:169], s[50:51]
	v_pk_mul_f32 v[244:245], v[152:153], s[50:51]
	v_pk_mul_f32 v[246:247], v[140:141], s[50:51]
	v_exp_f32_e32 v222, v222
	v_exp_f32_e32 v223, v223
	v_exp_f32_e32 v242, v242
	v_exp_f32_e32 v243, v243
	v_exp_f32_e32 v244, v244
	v_exp_f32_e32 v245, v245
	v_exp_f32_e32 v246, v246
	v_exp_f32_e32 v247, v247
	v_pk_add_f32 v[222:223], v[222:223], 1.0 op_sel_hi:[1,0]
	v_pk_add_f32 v[242:243], v[242:243], 1.0 op_sel_hi:[1,0]
	v_pk_add_f32 v[244:245], v[244:245], 1.0 op_sel_hi:[1,0]
	v_pk_add_f32 v[246:247], v[246:247], 1.0 op_sel_hi:[1,0]
	v_rcp_f32_e32 v222, v222
	v_rcp_f32_e32 v223, v223
	v_rcp_f32_e32 v242, v242
	v_rcp_f32_e32 v243, v243
	v_rcp_f32_e32 v244, v244
	v_rcp_f32_e32 v245, v245
	v_rcp_f32_e32 v246, v246
	v_rcp_f32_e32 v247, v247
	v_pk_mul_f32 v[184:185], v[184:185], v[222:223]
	v_pk_mul_f32 v[168:169], v[168:169], v[242:243]
	v_pk_mul_f32 v[152:153], v[152:153], v[244:245]
	v_pk_mul_f32 v[140:141], v[140:141], v[246:247]
	v_pk_mul_f32 v[184:185], v[184:185], v[180:181]
	v_pk_mul_f32 v[168:169], v[168:169], v[164:165]
	v_pk_mul_f32 v[152:153], v[152:153], v[148:149]
	v_pk_mul_f32 v[140:141], v[140:141], v[132:133]
	v_cvt_pk_bf16_f32 v194, v184, v185
	v_cvt_pk_bf16_f32 v178, v168, v169
	v_cvt_pk_bf16_f32 v162, v152, v153
	v_cvt_pk_bf16_f32 v146, v140, v141
	v_mov_b32_dpp v198, v142 row_shr:1 row_mask:0xf bank_mask:0xf bound_ctrl:1
	v_mov_b32_dpp v199, v143 row_shr:1 row_mask:0xf bank_mask:0xf bound_ctrl:1
	v_mov_b32_dpp v214, v134 row_shr:1 row_mask:0xf bank_mask:0xf bound_ctrl:1
	v_mov_b32_dpp v215, v135 row_shr:1 row_mask:0xf bank_mask:0xf bound_ctrl:1
	v_mov_b32_dpp v212, v154 row_shr:1 row_mask:0xf bank_mask:0xf bound_ctrl:1
	v_mov_b32_dpp v213, v155 row_shr:1 row_mask:0xf bank_mask:0xf bound_ctrl:1
	v_mov_b32_dpp v216, v150 row_shr:1 row_mask:0xf bank_mask:0xf bound_ctrl:1
	v_mov_b32_dpp v217, v151 row_shr:1 row_mask:0xf bank_mask:0xf bound_ctrl:1
	v_pk_fma_f32 v[142:143], v[142:143], v[86:87], v[82:83]
	v_pk_fma_f32 v[134:135], v[134:135], v[90:91], v[78:79]
	v_pk_fma_f32 v[142:143], v[154:155], v[66:67], v[142:143]
	v_pk_fma_f32 v[134:135], v[150:151], v[62:63], v[134:135]
	v_pk_fma_f32 v[142:143], v[170:171], v[58:59], v[142:143]
	v_pk_fma_f32 v[134:135], v[166:167], v[54:55], v[134:135]
	v_pk_fma_f32 v[154:155], v[154:155], v[86:87], v[82:83]
	v_pk_fma_f32 v[150:151], v[150:151], v[90:91], v[78:79]
	v_pk_fma_f32 v[154:155], v[170:171], v[66:67], v[154:155]
	v_pk_fma_f32 v[150:151], v[166:167], v[62:63], v[150:151]
	v_pk_fma_f32 v[154:155], v[186:187], v[58:59], v[154:155]
	v_pk_fma_f32 v[150:151], v[182:183], v[54:55], v[150:151]
	v_pk_fma_f32 v[170:171], v[170:171], v[86:87], v[82:83]
	v_pk_fma_f32 v[166:167], v[166:167], v[90:91], v[78:79]
	v_pk_fma_f32 v[170:171], v[186:187], v[66:67], v[170:171]
	v_pk_fma_f32 v[166:167], v[182:183], v[62:63], v[166:167]
	v_pk_fma_f32 v[170:171], v[198:199], v[58:59], v[170:171]
	v_pk_fma_f32 v[166:167], v[214:215], v[54:55], v[166:167]
	v_pk_fma_f32 v[186:187], v[186:187], v[86:87], v[82:83]
	v_pk_fma_f32 v[182:183], v[182:183], v[90:91], v[78:79]
	v_pk_fma_f32 v[186:187], v[198:199], v[66:67], v[186:187]
	v_pk_fma_f32 v[182:183], v[214:215], v[62:63], v[182:183]
	v_pk_fma_f32 v[186:187], v[212:213], v[58:59], v[186:187]
	v_pk_fma_f32 v[182:183], v[216:217], v[54:55], v[182:183]
	v_pk_mul_f32 v[222:223], v[186:187], s[50:51]
	v_pk_mul_f32 v[242:243], v[170:171], s[50:51]
	v_pk_mul_f32 v[244:245], v[154:155], s[50:51]
	v_pk_mul_f32 v[246:247], v[142:143], s[50:51]
	v_exp_f32_e32 v222, v222
	v_exp_f32_e32 v223, v223
	v_exp_f32_e32 v242, v242
	v_exp_f32_e32 v243, v243
	v_exp_f32_e32 v244, v244
	v_exp_f32_e32 v245, v245
	v_exp_f32_e32 v246, v246
	v_exp_f32_e32 v247, v247
	v_pk_add_f32 v[222:223], v[222:223], 1.0 op_sel_hi:[1,0]
	v_pk_add_f32 v[242:243], v[242:243], 1.0 op_sel_hi:[1,0]
	v_pk_add_f32 v[244:245], v[244:245], 1.0 op_sel_hi:[1,0]
	v_pk_add_f32 v[246:247], v[246:247], 1.0 op_sel_hi:[1,0]
	v_rcp_f32_e32 v222, v222
	v_rcp_f32_e32 v223, v223
	v_rcp_f32_e32 v242, v242
	v_rcp_f32_e32 v243, v243
	v_rcp_f32_e32 v244, v244
	v_rcp_f32_e32 v245, v245
	v_rcp_f32_e32 v246, v246
	v_rcp_f32_e32 v247, v247
	v_pk_mul_f32 v[186:187], v[186:187], v[222:223]
	v_pk_mul_f32 v[170:171], v[170:171], v[242:243]
	v_pk_mul_f32 v[154:155], v[154:155], v[244:245]
	v_pk_mul_f32 v[142:143], v[142:143], v[246:247]
	v_pk_mul_f32 v[186:187], v[186:187], v[182:183]
	v_pk_mul_f32 v[170:171], v[170:171], v[166:167]
	v_pk_mul_f32 v[154:155], v[154:155], v[150:151]
	v_pk_mul_f32 v[142:143], v[142:143], v[134:135]
	v_cvt_pk_bf16_f32 v195, v186, v187
	v_cvt_pk_bf16_f32 v179, v170, v171
	v_cvt_pk_bf16_f32 v163, v154, v155
	v_cvt_pk_bf16_f32 v147, v142, v143
	s_mov_b64 s[20:21], s[82:83]
	global_store_dwordx4 v240, v[192:195], s[20:21]
	s_add_u32 s20, s82, 0x1600
	s_addc_u32 s21, s83, 0
	global_store_dwordx4 v240, v[176:179], s[20:21]
	s_add_u32 s20, s82, 0x2c00
	s_addc_u32 s21, s83, 0
	global_store_dwordx4 v240, v[160:163], s[20:21]
	s_add_u32 s20, s82, 0x4200
	s_addc_u32 s21, s83, 0
	global_store_dwordx4 v240, v[144:147], s[20:21]
	v_mov_b32_dpp v198, v16 row_shr:1 row_mask:0xf bank_mask:0xf bound_ctrl:1
	v_mov_b32_dpp v199, v17 row_shr:1 row_mask:0xf bank_mask:0xf bound_ctrl:1
	v_mov_b32_dpp v214, v8 row_shr:1 row_mask:0xf bank_mask:0xf bound_ctrl:1
	v_mov_b32_dpp v215, v9 row_shr:1 row_mask:0xf bank_mask:0xf bound_ctrl:1
	v_mov_b32_dpp v212, v32 row_shr:1 row_mask:0xf bank_mask:0xf bound_ctrl:1
	v_mov_b32_dpp v213, v33 row_shr:1 row_mask:0xf bank_mask:0xf bound_ctrl:1
	v_mov_b32_dpp v216, v28 row_shr:1 row_mask:0xf bank_mask:0xf bound_ctrl:1
	v_mov_b32_dpp v217, v29 row_shr:1 row_mask:0xf bank_mask:0xf bound_ctrl:1
	v_pk_fma_f32 v[16:17], v[16:17], v[124:125], v[120:121]
	v_pk_fma_f32 v[8:9], v[8:9], v[128:129], v[116:117]
	v_pk_fma_f32 v[16:17], v[32:33], v[104:105], v[16:17]
	v_pk_fma_f32 v[8:9], v[28:29], v[100:101], v[8:9]
	v_pk_fma_f32 v[16:17], v[48:49], v[96:97], v[16:17]
	v_pk_fma_f32 v[8:9], v[44:45], v[92:93], v[8:9]
	v_pk_fma_f32 v[32:33], v[32:33], v[124:125], v[120:121]
	v_pk_fma_f32 v[28:29], v[28:29], v[128:129], v[116:117]
	v_pk_fma_f32 v[32:33], v[48:49], v[104:105], v[32:33]
	v_pk_fma_f32 v[28:29], v[44:45], v[100:101], v[28:29]
	v_pk_fma_f32 v[32:33], v[112:113], v[96:97], v[32:33]
	v_pk_fma_f32 v[28:29], v[108:109], v[92:93], v[28:29]
	v_pk_fma_f32 v[48:49], v[48:49], v[124:125], v[120:121]
	v_pk_fma_f32 v[44:45], v[44:45], v[128:129], v[116:117]
	v_pk_fma_f32 v[48:49], v[112:113], v[104:105], v[48:49]
	v_pk_fma_f32 v[44:45], v[108:109], v[100:101], v[44:45]
	v_pk_fma_f32 v[48:49], v[198:199], v[96:97], v[48:49]
	v_pk_fma_f32 v[44:45], v[214:215], v[92:93], v[44:45]
	v_pk_fma_f32 v[112:113], v[112:113], v[124:125], v[120:121]
	v_pk_fma_f32 v[108:109], v[108:109], v[128:129], v[116:117]
	v_pk_fma_f32 v[112:113], v[198:199], v[104:105], v[112:113]
	v_pk_fma_f32 v[108:109], v[214:215], v[100:101], v[108:109]
	v_pk_fma_f32 v[112:113], v[212:213], v[96:97], v[112:113]
	v_pk_fma_f32 v[108:109], v[216:217], v[92:93], v[108:109]
	v_pk_mul_f32 v[222:223], v[112:113], s[50:51]
	v_pk_mul_f32 v[242:243], v[48:49], s[50:51]
	v_pk_mul_f32 v[244:245], v[32:33], s[50:51]
	v_pk_mul_f32 v[246:247], v[16:17], s[50:51]
	v_exp_f32_e32 v222, v222
	v_exp_f32_e32 v223, v223
	v_exp_f32_e32 v242, v242
	v_exp_f32_e32 v243, v243
	v_exp_f32_e32 v244, v244
	v_exp_f32_e32 v245, v245
	v_exp_f32_e32 v246, v246
	v_exp_f32_e32 v247, v247
	v_pk_add_f32 v[222:223], v[222:223], 1.0 op_sel_hi:[1,0]
	v_pk_add_f32 v[242:243], v[242:243], 1.0 op_sel_hi:[1,0]
	v_pk_add_f32 v[244:245], v[244:245], 1.0 op_sel_hi:[1,0]
	v_pk_add_f32 v[246:247], v[246:247], 1.0 op_sel_hi:[1,0]
	v_rcp_f32_e32 v222, v222
	v_rcp_f32_e32 v223, v223
	v_rcp_f32_e32 v242, v242
	v_rcp_f32_e32 v243, v243
	v_rcp_f32_e32 v244, v244
	v_rcp_f32_e32 v245, v245
	v_rcp_f32_e32 v246, v246
	v_rcp_f32_e32 v247, v247
	v_pk_mul_f32 v[112:113], v[112:113], v[222:223]
	v_pk_mul_f32 v[48:49], v[48:49], v[242:243]
	v_pk_mul_f32 v[32:33], v[32:33], v[244:245]
	v_pk_mul_f32 v[16:17], v[16:17], v[246:247]
	v_pk_mul_f32 v[112:113], v[112:113], v[108:109]
	v_pk_mul_f32 v[48:49], v[48:49], v[44:45]
	v_pk_mul_f32 v[32:33], v[32:33], v[28:29]
	v_pk_mul_f32 v[16:17], v[16:17], v[8:9]
	v_cvt_pk_bf16_f32 v112, v112, v113
	v_cvt_pk_bf16_f32 v48, v48, v49
	v_cvt_pk_bf16_f32 v32, v32, v33
	v_cvt_pk_bf16_f32 v16, v16, v17
	v_mov_b32_dpp v198, v18 row_shr:1 row_mask:0xf bank_mask:0xf bound_ctrl:1
	v_mov_b32_dpp v199, v19 row_shr:1 row_mask:0xf bank_mask:0xf bound_ctrl:1
	v_mov_b32_dpp v214, v10 row_shr:1 row_mask:0xf bank_mask:0xf bound_ctrl:1
	v_mov_b32_dpp v215, v11 row_shr:1 row_mask:0xf bank_mask:0xf bound_ctrl:1
	v_mov_b32_dpp v212, v34 row_shr:1 row_mask:0xf bank_mask:0xf bound_ctrl:1
	v_mov_b32_dpp v213, v35 row_shr:1 row_mask:0xf bank_mask:0xf bound_ctrl:1
	v_mov_b32_dpp v216, v30 row_shr:1 row_mask:0xf bank_mask:0xf bound_ctrl:1
	v_mov_b32_dpp v217, v31 row_shr:1 row_mask:0xf bank_mask:0xf bound_ctrl:1
	v_pk_fma_f32 v[18:19], v[18:19], v[126:127], v[122:123]
	v_pk_fma_f32 v[10:11], v[10:11], v[130:131], v[118:119]
	v_pk_fma_f32 v[18:19], v[34:35], v[106:107], v[18:19]
	v_pk_fma_f32 v[10:11], v[30:31], v[102:103], v[10:11]
	v_pk_fma_f32 v[18:19], v[50:51], v[98:99], v[18:19]
	v_pk_fma_f32 v[10:11], v[46:47], v[94:95], v[10:11]
	v_pk_fma_f32 v[34:35], v[34:35], v[126:127], v[122:123]
	v_pk_fma_f32 v[30:31], v[30:31], v[130:131], v[118:119]
	v_pk_fma_f32 v[34:35], v[50:51], v[106:107], v[34:35]
	v_pk_fma_f32 v[30:31], v[46:47], v[102:103], v[30:31]
	v_pk_fma_f32 v[34:35], v[114:115], v[98:99], v[34:35]
	v_pk_fma_f32 v[30:31], v[110:111], v[94:95], v[30:31]
	v_pk_fma_f32 v[50:51], v[50:51], v[126:127], v[122:123]
	v_pk_fma_f32 v[46:47], v[46:47], v[130:131], v[118:119]
	v_pk_fma_f32 v[50:51], v[114:115], v[106:107], v[50:51]
	v_pk_fma_f32 v[46:47], v[110:111], v[102:103], v[46:47]
	v_pk_fma_f32 v[50:51], v[198:199], v[98:99], v[50:51]
	v_pk_fma_f32 v[46:47], v[214:215], v[94:95], v[46:47]
	v_pk_fma_f32 v[114:115], v[114:115], v[126:127], v[122:123]
	v_pk_fma_f32 v[110:111], v[110:111], v[130:131], v[118:119]
	v_pk_fma_f32 v[114:115], v[198:199], v[106:107], v[114:115]
	v_pk_fma_f32 v[110:111], v[214:215], v[102:103], v[110:111]
	v_pk_fma_f32 v[114:115], v[212:213], v[98:99], v[114:115]
	v_pk_fma_f32 v[110:111], v[216:217], v[94:95], v[110:111]
	v_pk_mul_f32 v[222:223], v[114:115], s[50:51]
	v_pk_mul_f32 v[242:243], v[50:51], s[50:51]
	v_pk_mul_f32 v[244:245], v[34:35], s[50:51]
	v_pk_mul_f32 v[246:247], v[18:19], s[50:51]
	v_exp_f32_e32 v222, v222
	v_exp_f32_e32 v223, v223
	v_exp_f32_e32 v242, v242
	v_exp_f32_e32 v243, v243
	v_exp_f32_e32 v244, v244
	v_exp_f32_e32 v245, v245
	v_exp_f32_e32 v246, v246
	v_exp_f32_e32 v247, v247
	v_pk_add_f32 v[222:223], v[222:223], 1.0 op_sel_hi:[1,0]
	v_pk_add_f32 v[242:243], v[242:243], 1.0 op_sel_hi:[1,0]
	v_pk_add_f32 v[244:245], v[244:245], 1.0 op_sel_hi:[1,0]
	v_pk_add_f32 v[246:247], v[246:247], 1.0 op_sel_hi:[1,0]
	v_rcp_f32_e32 v222, v222
	v_rcp_f32_e32 v223, v223
	v_rcp_f32_e32 v242, v242
	v_rcp_f32_e32 v243, v243
	v_rcp_f32_e32 v244, v244
	v_rcp_f32_e32 v245, v245
	v_rcp_f32_e32 v246, v246
	v_rcp_f32_e32 v247, v247
	v_pk_mul_f32 v[114:115], v[114:115], v[222:223]
	v_pk_mul_f32 v[50:51], v[50:51], v[242:243]
	v_pk_mul_f32 v[34:35], v[34:35], v[244:245]
	v_pk_mul_f32 v[18:19], v[18:19], v[246:247]
	v_pk_mul_f32 v[114:115], v[114:115], v[110:111]
	v_pk_mul_f32 v[50:51], v[50:51], v[46:47]
	v_pk_mul_f32 v[34:35], v[34:35], v[30:31]
	v_pk_mul_f32 v[18:19], v[18:19], v[10:11]
	v_cvt_pk_bf16_f32 v113, v114, v115
	v_cvt_pk_bf16_f32 v49, v50, v51
	v_cvt_pk_bf16_f32 v33, v34, v35
	v_cvt_pk_bf16_f32 v17, v18, v19
	v_mov_b32_dpp v198, v12 row_shr:1 row_mask:0xf bank_mask:0xf bound_ctrl:1
	v_mov_b32_dpp v199, v13 row_shr:1 row_mask:0xf bank_mask:0xf bound_ctrl:1
	v_mov_b32_dpp v214, v4 row_shr:1 row_mask:0xf bank_mask:0xf bound_ctrl:1
	v_mov_b32_dpp v215, v5 row_shr:1 row_mask:0xf bank_mask:0xf bound_ctrl:1
	v_mov_b32_dpp v212, v24 row_shr:1 row_mask:0xf bank_mask:0xf bound_ctrl:1
	v_mov_b32_dpp v213, v25 row_shr:1 row_mask:0xf bank_mask:0xf bound_ctrl:1
	v_mov_b32_dpp v216, v20 row_shr:1 row_mask:0xf bank_mask:0xf bound_ctrl:1
	v_mov_b32_dpp v217, v21 row_shr:1 row_mask:0xf bank_mask:0xf bound_ctrl:1
	v_pk_fma_f32 v[12:13], v[12:13], v[84:85], v[80:81]
	v_pk_fma_f32 v[4:5], v[4:5], v[88:89], v[76:77]
	v_pk_fma_f32 v[12:13], v[24:25], v[64:65], v[12:13]
	v_pk_fma_f32 v[4:5], v[20:21], v[60:61], v[4:5]
	v_pk_fma_f32 v[12:13], v[40:41], v[56:57], v[12:13]
	v_pk_fma_f32 v[4:5], v[36:37], v[52:53], v[4:5]
	v_pk_fma_f32 v[24:25], v[24:25], v[84:85], v[80:81]
	v_pk_fma_f32 v[20:21], v[20:21], v[88:89], v[76:77]
	v_pk_fma_f32 v[24:25], v[40:41], v[64:65], v[24:25]
	v_pk_fma_f32 v[20:21], v[36:37], v[60:61], v[20:21]
	v_pk_fma_f32 v[24:25], v[72:73], v[56:57], v[24:25]
	v_pk_fma_f32 v[20:21], v[68:69], v[52:53], v[20:21]
	v_pk_fma_f32 v[40:41], v[40:41], v[84:85], v[80:81]
	v_pk_fma_f32 v[36:37], v[36:37], v[88:89], v[76:77]
	v_pk_fma_f32 v[40:41], v[72:73], v[64:65], v[40:41]
	v_pk_fma_f32 v[36:37], v[68:69], v[60:61], v[36:37]
	v_pk_fma_f32 v[40:41], v[198:199], v[56:57], v[40:41]
	v_pk_fma_f32 v[36:37], v[214:215], v[52:53], v[36:37]
	v_pk_fma_f32 v[72:73], v[72:73], v[84:85], v[80:81]
	v_pk_fma_f32 v[68:69], v[68:69], v[88:89], v[76:77]
	v_pk_fma_f32 v[72:73], v[198:199], v[64:65], v[72:73]
	v_pk_fma_f32 v[68:69], v[214:215], v[60:61], v[68:69]
	v_pk_fma_f32 v[72:73], v[212:213], v[56:57], v[72:73]
	v_pk_fma_f32 v[68:69], v[216:217], v[52:53], v[68:69]
	v_pk_mul_f32 v[222:223], v[72:73], s[50:51]
	v_pk_mul_f32 v[242:243], v[40:41], s[50:51]
	v_pk_mul_f32 v[244:245], v[24:25], s[50:51]
	v_pk_mul_f32 v[246:247], v[12:13], s[50:51]
	v_exp_f32_e32 v222, v222
	v_exp_f32_e32 v223, v223
	v_exp_f32_e32 v242, v242
	v_exp_f32_e32 v243, v243
	v_exp_f32_e32 v244, v244
	v_exp_f32_e32 v245, v245
	v_exp_f32_e32 v246, v246
	v_exp_f32_e32 v247, v247
	v_pk_add_f32 v[222:223], v[222:223], 1.0 op_sel_hi:[1,0]
	v_pk_add_f32 v[242:243], v[242:243], 1.0 op_sel_hi:[1,0]
	v_pk_add_f32 v[244:245], v[244:245], 1.0 op_sel_hi:[1,0]
	v_pk_add_f32 v[246:247], v[246:247], 1.0 op_sel_hi:[1,0]
	v_rcp_f32_e32 v222, v222
	v_rcp_f32_e32 v223, v223
	v_rcp_f32_e32 v242, v242
	v_rcp_f32_e32 v243, v243
	v_rcp_f32_e32 v244, v244
	v_rcp_f32_e32 v245, v245
	v_rcp_f32_e32 v246, v246
	v_rcp_f32_e32 v247, v247
	v_pk_mul_f32 v[72:73], v[72:73], v[222:223]
	v_pk_mul_f32 v[40:41], v[40:41], v[242:243]
	v_pk_mul_f32 v[24:25], v[24:25], v[244:245]
	v_pk_mul_f32 v[12:13], v[12:13], v[246:247]
	v_pk_mul_f32 v[72:73], v[72:73], v[68:69]
	v_pk_mul_f32 v[40:41], v[40:41], v[36:37]
	v_pk_mul_f32 v[24:25], v[24:25], v[20:21]
	v_pk_mul_f32 v[12:13], v[12:13], v[4:5]
	v_cvt_pk_bf16_f32 v114, v72, v73
	v_cvt_pk_bf16_f32 v50, v40, v41
	v_cvt_pk_bf16_f32 v34, v24, v25
	v_cvt_pk_bf16_f32 v18, v12, v13
	v_mov_b32_dpp v198, v14 row_shr:1 row_mask:0xf bank_mask:0xf bound_ctrl:1
	v_mov_b32_dpp v199, v15 row_shr:1 row_mask:0xf bank_mask:0xf bound_ctrl:1
	v_mov_b32_dpp v214, v6 row_shr:1 row_mask:0xf bank_mask:0xf bound_ctrl:1
	v_mov_b32_dpp v215, v7 row_shr:1 row_mask:0xf bank_mask:0xf bound_ctrl:1
	v_mov_b32_dpp v212, v26 row_shr:1 row_mask:0xf bank_mask:0xf bound_ctrl:1
	v_mov_b32_dpp v213, v27 row_shr:1 row_mask:0xf bank_mask:0xf bound_ctrl:1
	v_mov_b32_dpp v216, v22 row_shr:1 row_mask:0xf bank_mask:0xf bound_ctrl:1
	v_mov_b32_dpp v217, v23 row_shr:1 row_mask:0xf bank_mask:0xf bound_ctrl:1
	v_pk_fma_f32 v[14:15], v[14:15], v[86:87], v[82:83]
	v_pk_fma_f32 v[6:7], v[6:7], v[90:91], v[78:79]
	v_pk_fma_f32 v[14:15], v[26:27], v[66:67], v[14:15]
	v_pk_fma_f32 v[6:7], v[22:23], v[62:63], v[6:7]
	v_pk_fma_f32 v[14:15], v[42:43], v[58:59], v[14:15]
	v_pk_fma_f32 v[6:7], v[38:39], v[54:55], v[6:7]
	v_pk_fma_f32 v[26:27], v[26:27], v[86:87], v[82:83]
	v_pk_fma_f32 v[22:23], v[22:23], v[90:91], v[78:79]
	v_pk_fma_f32 v[26:27], v[42:43], v[66:67], v[26:27]
	v_pk_fma_f32 v[22:23], v[38:39], v[62:63], v[22:23]
	v_pk_fma_f32 v[26:27], v[74:75], v[58:59], v[26:27]
	v_pk_fma_f32 v[22:23], v[70:71], v[54:55], v[22:23]
	v_pk_fma_f32 v[42:43], v[42:43], v[86:87], v[82:83]
	v_pk_fma_f32 v[38:39], v[38:39], v[90:91], v[78:79]
	v_pk_fma_f32 v[42:43], v[74:75], v[66:67], v[42:43]
	v_pk_fma_f32 v[38:39], v[70:71], v[62:63], v[38:39]
	v_pk_fma_f32 v[42:43], v[198:199], v[58:59], v[42:43]
	v_pk_fma_f32 v[38:39], v[214:215], v[54:55], v[38:39]
	v_pk_fma_f32 v[74:75], v[74:75], v[86:87], v[82:83]
	v_pk_fma_f32 v[70:71], v[70:71], v[90:91], v[78:79]
	v_pk_fma_f32 v[74:75], v[198:199], v[66:67], v[74:75]
	v_pk_fma_f32 v[70:71], v[214:215], v[62:63], v[70:71]
	v_pk_fma_f32 v[74:75], v[212:213], v[58:59], v[74:75]
	v_pk_fma_f32 v[70:71], v[216:217], v[54:55], v[70:71]
	v_pk_mul_f32 v[222:223], v[74:75], s[50:51]
	v_pk_mul_f32 v[242:243], v[42:43], s[50:51]
	v_pk_mul_f32 v[244:245], v[26:27], s[50:51]
	v_pk_mul_f32 v[246:247], v[14:15], s[50:51]
	v_exp_f32_e32 v222, v222
	v_exp_f32_e32 v223, v223
	v_exp_f32_e32 v242, v242
	v_exp_f32_e32 v243, v243
	v_exp_f32_e32 v244, v244
	v_exp_f32_e32 v245, v245
	v_exp_f32_e32 v246, v246
	v_exp_f32_e32 v247, v247
	v_pk_add_f32 v[222:223], v[222:223], 1.0 op_sel_hi:[1,0]
	v_pk_add_f32 v[242:243], v[242:243], 1.0 op_sel_hi:[1,0]
	v_pk_add_f32 v[244:245], v[244:245], 1.0 op_sel_hi:[1,0]
	v_pk_add_f32 v[246:247], v[246:247], 1.0 op_sel_hi:[1,0]
	v_rcp_f32_e32 v222, v222
	v_rcp_f32_e32 v223, v223
	v_rcp_f32_e32 v242, v242
	v_rcp_f32_e32 v243, v243
	v_rcp_f32_e32 v244, v244
	v_rcp_f32_e32 v245, v245
	v_rcp_f32_e32 v246, v246
	v_rcp_f32_e32 v247, v247
	v_pk_mul_f32 v[74:75], v[74:75], v[222:223]
	v_pk_mul_f32 v[42:43], v[42:43], v[242:243]
	v_pk_mul_f32 v[26:27], v[26:27], v[244:245]
	v_pk_mul_f32 v[14:15], v[14:15], v[246:247]
	v_pk_mul_f32 v[74:75], v[74:75], v[70:71]
	v_pk_mul_f32 v[42:43], v[42:43], v[38:39]
	v_pk_mul_f32 v[26:27], v[26:27], v[22:23]
	v_pk_mul_f32 v[14:15], v[14:15], v[6:7]
	v_cvt_pk_bf16_f32 v115, v74, v75
	v_cvt_pk_bf16_f32 v51, v42, v43
	v_cvt_pk_bf16_f32 v35, v26, v27
	v_cvt_pk_bf16_f32 v19, v14, v15
	s_add_u32 s20, s82, 0xb0000
	s_addc_u32 s21, s83, 0
	global_store_dwordx4 v240, v[112:115], s[20:21]
	s_add_u32 s20, s82, 0xb1600
	s_addc_u32 s21, s83, 0
	global_store_dwordx4 v240, v[48:51], s[20:21]
	s_add_u32 s20, s82, 0xb2c00
	s_addc_u32 s21, s83, 0
	global_store_dwordx4 v240, v[32:35], s[20:21]
	s_add_u32 s20, s82, 0xb4200
	s_addc_u32 s21, s83, 0
	global_store_dwordx4 v240, v[16:19], s[20:21]
	s_mov_b64 s[50:51], -1
	s_branch .LBB0_76
